# scan MFMA-stage epilogue rewritten: 16-wide ILP, packed f32 silu gate, SGPR-stepped store bases
# speedup vs baseline: 1.0141x; 1.0013x over previous
.LBB0_821:
	v_mov_b32_e32 v34, v155
	s_or_b64 s[0:1], s[46:47], s[0:1]
	v_ashrrev_i32_e32 v35, 3, v34
	v_and_b32_e32 v32, 0xffffc, v35
	v_and_b32_e32 v33, 31, v34
	v_add_lshl_u32 v32, v32, s6, 11
	v_or3_b32 v32, v32, s28, v33
	v_or_b32_e32 v36, s22, v33
	v_add_u32_e32 v33, s27, v35
	v_lshlrev_b32_e32 v35, 1, v35
	v_mul_u32_u24_e32 v36, 0x110, v36
	v_and_b32_e32 v35, 8, v35
	v_lshrrev_b32_e32 v34, 1, v34
	v_add3_u32 v35, 0, v36, v35
	v_lshrrev_b32_e32 v44, 3, v33
	v_lshlrev_b32_e32 v32, 1, v32
	v_add_u32_e32 v45, 1, v44
	v_add_u32_e32 v46, 2, v44
	v_add_u32_e32 v47, 3, v44
	v_xor_b32_e32 v44, v44, v34
	v_xor_b32_e32 v45, v45, v34
	v_xor_b32_e32 v46, v46, v34
	v_xor_b32_e32 v47, v47, v34
	v_and_b32_e32 v44, 15, v44
	v_and_b32_e32 v45, 15, v45
	v_and_b32_e32 v46, 15, v46
	v_and_b32_e32 v47, 15, v47
	v_lshl_add_u32 v44, v44, 4, v35
	v_lshl_add_u32 v45, v45, 4, v35
	v_lshl_add_u32 v46, v46, 4, v35
	v_lshl_add_u32 v47, v47, 4, v35
	ds_read_b64 v[36:37], v44
	ds_read_b64 v[38:39], v45
	ds_read_b64 v[40:41], v46
	ds_read_b64 v[42:43], v47
	s_add_i32 s35, s35, 1
	s_waitcnt vmcnt(0)
	v_lshlrev_b32_e32 v175, 16, v175
	v_lshlrev_b32_e32 v174, 16, v174
	v_lshlrev_b32_e32 v173, 16, v173
	v_lshlrev_b32_e32 v172, 16, v172
	v_lshlrev_b32_e32 v171, 16, v171
	v_lshlrev_b32_e32 v170, 16, v170
	v_lshlrev_b32_e32 v169, 16, v169
	v_lshlrev_b32_e32 v168, 16, v168
	v_lshlrev_b32_e32 v167, 16, v167
	v_lshlrev_b32_e32 v166, 16, v166
	v_lshlrev_b32_e32 v165, 16, v165
	v_lshlrev_b32_e32 v164, 16, v164
	v_lshlrev_b32_e32 v163, 16, v163
	v_lshlrev_b32_e32 v162, 16, v162
	v_lshlrev_b32_e32 v242, 16, v146
	v_lshlrev_b32_e32 v243, 16, v51
	v_pk_mul_f32 v[184:185], v[174:175], s[78:79] op_sel_hi:[1,0]
	v_pk_mul_f32 v[186:187], v[172:173], s[78:79] op_sel_hi:[1,0]
	v_pk_mul_f32 v[188:189], v[170:171], s[78:79] op_sel_hi:[1,0]
	v_pk_mul_f32 v[190:191], v[168:169], s[78:79] op_sel_hi:[1,0]
	v_pk_mul_f32 v[192:193], v[166:167], s[78:79] op_sel_hi:[1,0]
	v_pk_mul_f32 v[194:195], v[164:165], s[78:79] op_sel_hi:[1,0]
	v_pk_mul_f32 v[196:197], v[162:163], s[78:79] op_sel_hi:[1,0]
	v_pk_mul_f32 v[244:245], v[242:243], s[78:79] op_sel_hi:[1,0]
	v_exp_f32_e32 v184, v184
	v_exp_f32_e32 v185, v185
	v_exp_f32_e32 v186, v186
	v_exp_f32_e32 v187, v187
	v_exp_f32_e32 v188, v188
	v_exp_f32_e32 v189, v189
	v_exp_f32_e32 v190, v190
	v_exp_f32_e32 v191, v191
	v_exp_f32_e32 v192, v192
	v_exp_f32_e32 v193, v193
	v_exp_f32_e32 v194, v194
	v_exp_f32_e32 v195, v195
	v_exp_f32_e32 v196, v196
	v_exp_f32_e32 v197, v197
	v_exp_f32_e32 v244, v244
	v_exp_f32_e32 v245, v245
	s_waitcnt lgkmcnt(0)
	v_lshlrev_b32_e32 v96, 16, v36
	v_and_b32_e32 v97, 0xffff0000, v36
	v_lshlrev_b32_e32 v98, 16, v37
	v_and_b32_e32 v99, 0xffff0000, v37
	v_lshlrev_b32_e32 v100, 16, v38
	v_and_b32_e32 v101, 0xffff0000, v38
	v_lshlrev_b32_e32 v102, 16, v39
	v_and_b32_e32 v103, 0xffff0000, v39
	v_lshlrev_b32_e32 v104, 16, v40
	v_and_b32_e32 v105, 0xffff0000, v40
	v_lshlrev_b32_e32 v106, 16, v41
	v_and_b32_e32 v107, 0xffff0000, v41
	v_lshlrev_b32_e32 v108, 16, v42
	v_and_b32_e32 v109, 0xffff0000, v42
	v_lshlrev_b32_e32 v110, 16, v43
	v_and_b32_e32 v111, 0xffff0000, v43
	v_pk_add_f32 v[184:185], v[184:185], 1.0 op_sel_hi:[1,0]
	v_pk_add_f32 v[186:187], v[186:187], 1.0 op_sel_hi:[1,0]
	v_pk_add_f32 v[188:189], v[188:189], 1.0 op_sel_hi:[1,0]
	v_pk_add_f32 v[190:191], v[190:191], 1.0 op_sel_hi:[1,0]
	v_pk_add_f32 v[192:193], v[192:193], 1.0 op_sel_hi:[1,0]
	v_pk_add_f32 v[194:195], v[194:195], 1.0 op_sel_hi:[1,0]
	v_pk_add_f32 v[196:197], v[196:197], 1.0 op_sel_hi:[1,0]
	v_pk_add_f32 v[244:245], v[244:245], 1.0 op_sel_hi:[1,0]
	v_pk_fma_f32 v[16:17], v[96:97], v[148:149], v[16:17] op_sel_hi:[1,0,1]
	v_pk_fma_f32 v[18:19], v[98:99], v[148:149], v[18:19] op_sel_hi:[1,0,1]
	v_pk_fma_f32 v[20:21], v[100:101], v[148:149], v[20:21] op_sel_hi:[1,0,1]
	v_pk_fma_f32 v[22:23], v[102:103], v[148:149], v[22:23] op_sel_hi:[1,0,1]
	v_pk_fma_f32 v[24:25], v[104:105], v[148:149], v[24:25] op_sel_hi:[1,0,1]
	v_pk_fma_f32 v[26:27], v[106:107], v[148:149], v[26:27] op_sel_hi:[1,0,1]
	v_pk_fma_f32 v[28:29], v[108:109], v[148:149], v[28:29] op_sel_hi:[1,0,1]
	v_pk_fma_f32 v[30:31], v[110:111], v[148:149], v[30:31] op_sel_hi:[1,0,1]
	v_rcp_f32_e32 v184, v184
	v_rcp_f32_e32 v185, v185
	v_rcp_f32_e32 v186, v186
	v_rcp_f32_e32 v187, v187
	v_rcp_f32_e32 v188, v188
	v_rcp_f32_e32 v189, v189
	v_rcp_f32_e32 v190, v190
	v_rcp_f32_e32 v191, v191
	v_rcp_f32_e32 v192, v192
	v_rcp_f32_e32 v193, v193
	v_rcp_f32_e32 v194, v194
	v_rcp_f32_e32 v195, v195
	v_rcp_f32_e32 v196, v196
	v_rcp_f32_e32 v197, v197
	v_rcp_f32_e32 v244, v244
	v_rcp_f32_e32 v245, v245
	s_nop 0
	v_pk_mul_f32 v[184:185], v[174:175], v[184:185]
	v_pk_mul_f32 v[186:187], v[172:173], v[186:187]
	v_pk_mul_f32 v[188:189], v[170:171], v[188:189]
	v_pk_mul_f32 v[190:191], v[168:169], v[190:191]
	v_pk_mul_f32 v[192:193], v[166:167], v[192:193]
	v_pk_mul_f32 v[194:195], v[164:165], v[194:195]
	v_pk_mul_f32 v[196:197], v[162:163], v[196:197]
	v_pk_mul_f32 v[244:245], v[242:243], v[244:245]
	v_pk_mul_f32 v[16:17], v[16:17], v[184:185] op_sel:[0,1] op_sel_hi:[1,0]
	v_pk_mul_f32 v[18:19], v[18:19], v[186:187] op_sel:[0,1] op_sel_hi:[1,0]
	v_pk_mul_f32 v[20:21], v[20:21], v[188:189] op_sel:[0,1] op_sel_hi:[1,0]
	v_pk_mul_f32 v[22:23], v[22:23], v[190:191] op_sel:[0,1] op_sel_hi:[1,0]
	v_pk_mul_f32 v[24:25], v[24:25], v[192:193] op_sel:[0,1] op_sel_hi:[1,0]
	v_pk_mul_f32 v[26:27], v[26:27], v[194:195] op_sel:[0,1] op_sel_hi:[1,0]
	v_pk_mul_f32 v[28:29], v[28:29], v[196:197] op_sel:[0,1] op_sel_hi:[1,0]
	v_pk_mul_f32 v[30:31], v[30:31], v[244:245]
	v_cvt_pk_bf16_f32 v16, v16, v49
	v_cvt_pk_bf16_f32 v17, v17, v49
	v_cvt_pk_bf16_f32 v18, v18, v49
	v_cvt_pk_bf16_f32 v19, v19, v49
	v_cvt_pk_bf16_f32 v20, v20, v49
	v_cvt_pk_bf16_f32 v21, v21, v49
	v_cvt_pk_bf16_f32 v22, v22, v49
	v_cvt_pk_bf16_f32 v23, v23, v49
	v_cvt_pk_bf16_f32 v24, v24, v49
	v_cvt_pk_bf16_f32 v25, v25, v49
	v_cvt_pk_bf16_f32 v26, v26, v49
	v_cvt_pk_bf16_f32 v27, v27, v49
	v_cvt_pk_bf16_f32 v28, v28, v49
	v_cvt_pk_bf16_f32 v29, v29, v49
	v_cvt_pk_bf16_f32 v30, v30, v49
	v_cvt_pk_bf16_f32 v31, v31, v49
	global_store_short v32, v16, s[70:71]
	s_add_u32 s100, s70, 0x1000
	s_addc_u32 s101, s71, 0
	global_store_short v32, v17, s[100:101]
	s_add_u32 s100, s70, 0x2000
	s_addc_u32 s101, s71, 0
	global_store_short v32, v18, s[100:101]
	s_add_u32 s100, s70, 0x3000
	s_addc_u32 s101, s71, 0
	global_store_short v32, v19, s[100:101]
	s_add_u32 s100, s70, 0x8000
	s_addc_u32 s101, s71, 0
	global_store_short v32, v20, s[100:101]
	s_add_u32 s100, s70, 0x9000
	s_addc_u32 s101, s71, 0
	global_store_short v32, v21, s[100:101]
	s_add_u32 s100, s70, 0xa000
	s_addc_u32 s101, s71, 0
	global_store_short v32, v22, s[100:101]
	s_add_u32 s100, s70, 0xb000
	s_addc_u32 s101, s71, 0
	global_store_short v32, v23, s[100:101]
	s_add_u32 s100, s70, 0x10000
	s_addc_u32 s101, s71, 0
	global_store_short v32, v24, s[100:101]
	s_add_u32 s100, s70, 0x11000
	s_addc_u32 s101, s71, 0
	global_store_short v32, v25, s[100:101]
	s_add_u32 s100, s70, 0x12000
	s_addc_u32 s101, s71, 0
	global_store_short v32, v26, s[100:101]
	s_add_u32 s100, s70, 0x13000
	s_addc_u32 s101, s71, 0
	global_store_short v32, v27, s[100:101]
	s_add_u32 s100, s70, 0x18000
	s_addc_u32 s101, s71, 0
	global_store_short v32, v28, s[100:101]
	s_add_u32 s100, s70, 0x19000
	s_addc_u32 s101, s71, 0
	global_store_short v32, v29, s[100:101]
	s_add_u32 s100, s70, 0x1a000
	s_addc_u32 s101, s71, 0
	global_store_short v32, v30, s[100:101]
	s_add_u32 s100, s70, 0x1b000
	s_addc_u32 s101, s71, 0
	global_store_short v32, v31, s[100:101]
	s_and_b64 vcc, exec, s[0:1]
	s_cbranch_vccnz .LBB0_780
	v_add_f32_e32 v146, v149, v156
	v_mov_b32_e32 v16, v155
	v_cmp_nlt_f32_e32 vcc, s19, v146
	s_and_saveexec_b64 s[0:1], vcc
	s_cbranch_execz .LBB0_824
	v_mul_f32_e32 v17, 0x3fb8aa3b, v146
	v_exp_f32_e32 v17, v17
	s_mov_b32 s6, 0x3f317218
	v_add_f32_e32 v20, 1.0, v17
	v_frexp_mant_f32_e32 v22, v20
	v_cvt_f64_f32_e32 v[18:19], v20
	v_frexp_exp_i32_f64_e32 v18, v[18:19]
	v_cmp_gt_f32_e32 vcc, s64, v22
	v_add_f32_e32 v21, -1.0, v20
	v_sub_f32_e32 v23, v21, v20
	v_subbrev_co_u32_e32 v26, vcc, 0, v18, vcc
	v_sub_u32_e32 v18, 0, v26
	v_sub_f32_e32 v21, v17, v21
	v_add_f32_e32 v23, 1.0, v23
	v_ldexp_f32 v19, v20, v18
	v_add_f32_e32 v21, v21, v23
	v_add_f32_e32 v20, -1.0, v19
	v_add_f32_e32 v22, 1.0, v19
	v_ldexp_f32 v18, v21, v18
	v_add_f32_e32 v21, 1.0, v20
	v_add_f32_e32 v23, -1.0, v22
	v_sub_f32_e32 v21, v19, v21
	v_sub_f32_e32 v19, v19, v23
	v_add_f32_e32 v21, v18, v21
	v_add_f32_e32 v18, v18, v19
	v_add_f32_e32 v27, v22, v18
	v_rcp_f32_e32 v29, v27
	v_sub_f32_e32 v19, v27, v22
	v_sub_f32_e32 v28, v18, v19
	v_add_f32_e32 v19, v20, v21
	v_mul_f32_e32 v31, v19, v29
	v_sub_f32_e32 v18, v19, v20
	v_mul_f32_e32 v20, v27, v31
	v_fma_f32 v22, v31, v27, -v20
	v_fmac_f32_e32 v22, v31, v28
	v_sub_f32_e32 v30, v21, v18
	v_add_f32_e32 v18, v20, v22
	v_sub_f32_e32 v21, v19, v18
	v_pk_add_f32 v[24:25], v[18:19], v[20:21] neg_lo:[0,1] neg_hi:[0,1]
	v_mov_b32_e32 v23, v18
	v_pk_add_f32 v[18:19], v[24:25], v[22:23] neg_lo:[0,1] neg_hi:[0,1]
	s_nop 0
	v_add_f32_e32 v19, v30, v19
	v_add_f32_e32 v18, v18, v19
	v_add_f32_e32 v19, v21, v18
	v_mul_f32_e32 v30, v29, v19
	v_mul_f32_e32 v20, v27, v30
	v_fma_f32 v22, v30, v27, -v20
	v_fmac_f32_e32 v22, v30, v28
	v_sub_f32_e32 v21, v21, v19
	v_add_f32_e32 v27, v18, v21
	v_add_f32_e32 v18, v20, v22
	v_sub_f32_e32 v21, v19, v18
	v_pk_add_f32 v[24:25], v[18:19], v[20:21] neg_lo:[0,1] neg_hi:[0,1]
	v_mov_b32_e32 v23, v18
	v_pk_add_f32 v[18:19], v[24:25], v[22:23] neg_lo:[0,1] neg_hi:[0,1]
	s_nop 0
	v_add_f32_e32 v19, v27, v19
	v_add_f32_e32 v18, v18, v19
	v_add_f32_e32 v19, v31, v30
	v_add_f32_e32 v18, v21, v18
	v_sub_f32_e32 v20, v19, v31
	v_mul_f32_e32 v18, v29, v18
	v_sub_f32_e32 v20, v30, v20
	v_add_f32_e32 v20, v20, v18
	v_add_f32_e32 v22, v19, v20
	v_mul_f32_e32 v23, v22, v22
	v_fmamk_f32 v18, v23, 0x3e9b6dac, v236
	v_fmaak_f32 v207, v23, v18, 0x3f2aaada
	v_cvt_f32_i32_e32 v18, v26
	v_sub_f32_e32 v19, v22, v19
	v_sub_f32_e32 v19, v20, v19
	v_ldexp_f32 v24, v19, 1
	v_mul_f32_e32 v19, v22, v23
	v_ldexp_f32 v21, v22, 1
	v_pk_mul_f32 v[22:23], v[18:19], v[206:207]
	s_nop 0
	v_fma_f32 v20, v18, s6, -v22
	v_fmac_f32_e32 v20, 0xb102e308, v18
	v_pk_add_f32 v[18:19], v[22:23], v[20:21]
	s_mov_b32 s6, 0x7f800000
	v_sub_f32_e32 v21, v19, v21
	v_sub_f32_e32 v21, v23, v21
	v_add_f32_e32 v25, v24, v21
	v_mov_b32_e32 v24, v22
	v_pk_add_f32 v[22:23], v[18:19], v[22:23] neg_lo:[0,1] neg_hi:[0,1]
	v_pk_add_f32 v[26:27], v[18:19], v[24:25]
	v_mov_b32_e32 v21, v18
	v_mov_b32_e32 v23, v27
	v_pk_add_f32 v[28:29], v[20:21], v[22:23] neg_lo:[0,1] neg_hi:[0,1]
	v_pk_add_f32 v[20:21], v[20:21], v[22:23]
	v_mov_b32_e32 v24, v25
	v_pk_add_f32 v[22:23], v[20:21], v[18:19] op_sel:[1,0] op_sel_hi:[0,1] neg_lo:[0,1] neg_hi:[0,1]
	v_pk_add_f32 v[30:31], v[26:27], v[22:23] op_sel_hi:[1,0] neg_lo:[0,1] neg_hi:[0,1]
	v_mov_b32_e32 v26, v27
	v_mov_b32_e32 v27, v21
	v_pk_mov_b32 v[22:23], v[18:19], v[22:23] op_sel:[1,0]
	v_mov_b32_e32 v25, v18
	v_pk_add_f32 v[22:23], v[26:27], v[22:23] neg_lo:[0,1] neg_hi:[0,1]
	v_mov_b32_e32 v30, v28
	v_pk_add_f32 v[18:19], v[24:25], v[22:23] neg_lo:[0,1] neg_hi:[0,1]
	v_mov_b32_e32 v29, v21
	v_pk_add_f32 v[22:23], v[30:31], v[18:19]
	v_cmp_neq_f32_e32 vcc, s6, v17
	v_pk_add_f32 v[24:25], v[22:23], v[22:23] op_sel:[0,1] op_sel_hi:[1,0]
	s_mov_b32 s6, 0x33800000
	v_pk_add_f32 v[20:21], v[20:21], v[24:25] op_sel:[1,0] op_sel_hi:[0,1]
	v_mov_b32_e32 v23, v20
	v_pk_add_f32 v[26:27], v[22:23], v[28:29] neg_lo:[0,1] neg_hi:[0,1]
	v_mov_b32_e32 v19, v24
	v_sub_f32_e32 v21, v22, v26
	v_pk_add_f32 v[18:19], v[18:19], v[26:27] neg_lo:[0,1] neg_hi:[0,1]
	v_sub_f32_e32 v21, v28, v21
	v_add_f32_e32 v18, v18, v21
	v_add_f32_e32 v18, v18, v19
	v_add_f32_e32 v18, v20, v18
	v_cndmask_b32_e32 v18, v237, v18, vcc
	v_cmp_ngt_f32_e32 vcc, -1.0, v17
	s_nop 1
	v_cndmask_b32_e32 v18, v238, v18, vcc
	v_cmp_neq_f32_e32 vcc, -1.0, v17
	s_nop 1
	v_cndmask_b32_e32 v18, v239, v18, vcc
	v_cmp_lt_f32_e64 vcc, |v17|, s6
	s_nop 1
	v_cndmask_b32_e32 v146, v18, v17, vcc
